# P1 K-loop DMA issue rebalance: one L2-resident weight piece moved from the 6-DMA second load segment to the third (5+3), second segment wait vmcnt(7)
# baseline (speedup 1.0000x reference)
.LBB0_170:
	s_add_u32 s10, s8, 0xfffc0080
	s_addc_u32 s11, s9, -1
	s_add_i32 s30, 0, 0x10000
	s_cmp_eq_u32 s29, 12
	s_cselect_b32 s13, s3, s11
	s_cselect_b32 s12, s24, s10
	v_add_u32_e32 v0, s30, v197
	s_cselect_b32 s11, s25, s28
	s_cselect_b32 s10, s26, s27
	s_add_i32 s31, 0, 0x14000
	ds_read_b128 v[130:133], v0
	ds_read_b128 v[134:137], v0 offset:1024
	ds_read_b128 v[138:141], v0 offset:2048
	ds_read_b128 v[142:145], v0 offset:3072
	v_add_u32_e32 v0, s31, v197
	ds_read_b128 v[170:173], v0
	ds_read_b128 v[174:177], v0 offset:1024
	ds_read_b128 v[202:205], v0 offset:2048
	ds_read_b128 v[206:209], v0 offset:3072
	s_add_i32 m0, s59, 0xc000
	ds_read_b128 v[210:213], v200
	ds_read_b128 v[216:219], v200 offset:1024
	ds_read_b128 v[220:223], v200 offset:2048
	ds_read_b128 v[224:227], v200 offset:3072
	ds_read_b128 v[228:231], v200 offset:4096
	ds_read_b128 v[232:235], v200 offset:5120
	ds_read_b128 v[236:239], v200 offset:6144
	ds_read_b128 v[240:243], v200 offset:7168
	global_load_lds_dwordx4 v166, s[8:9]
	s_add_i32 m0, s59, 0xe000
	s_nop 0
	global_load_lds_dwordx4 v168, s[8:9]
	s_waitcnt vmcnt(8)
	s_waitcnt lgkmcnt(0)
	s_barrier
	s_setprio 1
	s_waitcnt lgkmcnt(0)
	v_mfma_f32_16x16x32_bf16 v[126:129], v[130:133], v[210:213], v[126:129]
	v_mfma_f32_16x16x32_bf16 v[122:125], v[138:141], v[210:213], v[122:125]
	v_mfma_f32_16x16x32_bf16 v[110:113], v[130:133], v[220:223], v[110:113]
	v_mfma_f32_16x16x32_bf16 v[106:109], v[138:141], v[220:223], v[106:109]
	v_mfma_f32_16x16x32_bf16 v[94:97], v[130:133], v[228:231], v[94:97]
	v_mfma_f32_16x16x32_bf16 v[90:93], v[138:141], v[228:231], v[90:93]
	v_mfma_f32_16x16x32_bf16 v[78:81], v[130:133], v[236:239], v[78:81]
	v_mfma_f32_16x16x32_bf16 v[74:77], v[138:141], v[236:239], v[74:77]
	v_mfma_f32_16x16x32_bf16 v[126:129], v[134:137], v[216:219], v[126:129]
	v_mfma_f32_16x16x32_bf16 v[122:125], v[142:145], v[216:219], v[122:125]
	v_mfma_f32_16x16x32_bf16 v[110:113], v[134:137], v[224:227], v[110:113]
	v_mfma_f32_16x16x32_bf16 v[106:109], v[142:145], v[224:227], v[106:109]
	v_mfma_f32_16x16x32_bf16 v[94:97], v[134:137], v[232:235], v[94:97]
	v_mfma_f32_16x16x32_bf16 v[90:93], v[142:145], v[232:235], v[90:93]
	v_mfma_f32_16x16x32_bf16 v[78:81], v[134:137], v[240:243], v[78:81]
	v_mfma_f32_16x16x32_bf16 v[74:77], v[142:145], v[240:243], v[74:77]
	s_setprio 0
	s_setprio 1
	v_mfma_f32_16x16x32_bf16 v[118:121], v[170:173], v[210:213], v[118:121]
	v_mfma_f32_16x16x32_bf16 v[114:117], v[202:205], v[210:213], v[114:117]
	v_mfma_f32_16x16x32_bf16 v[102:105], v[170:173], v[220:223], v[102:105]
	v_mfma_f32_16x16x32_bf16 v[98:101], v[202:205], v[220:223], v[98:101]
	v_mfma_f32_16x16x32_bf16 v[86:89], v[170:173], v[228:231], v[86:89]
	v_mfma_f32_16x16x32_bf16 v[82:85], v[202:205], v[228:231], v[82:85]
	v_mfma_f32_16x16x32_bf16 v[70:73], v[170:173], v[236:239], v[70:73]
	v_mfma_f32_16x16x32_bf16 v[66:69], v[202:205], v[236:239], v[66:69]
	v_mfma_f32_16x16x32_bf16 v[118:121], v[174:177], v[216:219], v[118:121]
	v_mfma_f32_16x16x32_bf16 v[114:117], v[206:209], v[216:219], v[114:117]
	v_mfma_f32_16x16x32_bf16 v[102:105], v[174:177], v[224:227], v[102:105]
	v_mfma_f32_16x16x32_bf16 v[98:101], v[206:209], v[224:227], v[98:101]
	v_mfma_f32_16x16x32_bf16 v[86:89], v[174:177], v[232:235], v[86:89]
	v_mfma_f32_16x16x32_bf16 v[82:85], v[206:209], v[232:235], v[82:85]
	v_mfma_f32_16x16x32_bf16 v[70:73], v[174:177], v[240:243], v[70:73]
	v_mfma_f32_16x16x32_bf16 v[66:69], v[206:209], v[240:243], v[66:69]
	s_setprio 0
	s_barrier
	s_add_i32 s30, s30, s61
	s_mov_b32 m0, s30
	ds_read_b128 v[210:213], v200 offset:16384
	ds_read_b128 v[216:219], v200 offset:17408
	ds_read_b128 v[220:223], v200 offset:18432
	ds_read_b128 v[224:227], v200 offset:19456
	ds_read_b128 v[228:231], v200 offset:20480
	ds_read_b128 v[232:235], v200 offset:21504
	ds_read_b128 v[236:239], v200 offset:22528
	ds_read_b128 v[240:243], v200 offset:23552
	global_load_lds_dwordx4 v154, s[10:11]
	s_add_i32 m0, s30, 0x2000
	s_add_u32 s42, s10, 0x40000
	s_addc_u32 s43, s11, 0
	s_add_i32 s30, s31, s61
	global_load_lds_dwordx4 v158, s[10:11]
	s_mov_b32 m0, s30
	s_nop 0
	global_load_lds_dwordx4 v154, s[42:43]
	s_mov_b32 m0, s59
	s_nop 0
	global_load_lds_dwordx4 v152, s[12:13]
	s_mov_b32 m0, s62
	s_nop 0
	global_load_lds_dwordx4 v156, s[12:13]
	s_waitcnt vmcnt(7)
	s_waitcnt lgkmcnt(0)
	s_barrier
	s_setprio 1
	s_waitcnt lgkmcnt(0)
	v_mfma_f32_16x16x32_bf16 v[62:65], v[130:133], v[210:213], v[62:65]
	v_mfma_f32_16x16x32_bf16 v[58:61], v[138:141], v[210:213], v[58:61]
	v_mfma_f32_16x16x32_bf16 v[46:49], v[130:133], v[220:223], v[46:49]
	v_mfma_f32_16x16x32_bf16 v[42:45], v[138:141], v[220:223], v[42:45]
	v_mfma_f32_16x16x32_bf16 v[30:33], v[130:133], v[228:231], v[30:33]
	v_mfma_f32_16x16x32_bf16 v[26:29], v[138:141], v[228:231], v[26:29]
	v_mfma_f32_16x16x32_bf16 v[14:17], v[130:133], v[236:239], v[14:17]
	v_mfma_f32_16x16x32_bf16 v[10:13], v[138:141], v[236:239], v[10:13]
	v_mfma_f32_16x16x32_bf16 v[62:65], v[134:137], v[216:219], v[62:65]
	v_mfma_f32_16x16x32_bf16 v[58:61], v[142:145], v[216:219], v[58:61]
	v_mfma_f32_16x16x32_bf16 v[46:49], v[134:137], v[224:227], v[46:49]
	v_mfma_f32_16x16x32_bf16 v[42:45], v[142:145], v[224:227], v[42:45]
	v_mfma_f32_16x16x32_bf16 v[30:33], v[134:137], v[232:235], v[30:33]
	v_mfma_f32_16x16x32_bf16 v[26:29], v[142:145], v[232:235], v[26:29]
	v_mfma_f32_16x16x32_bf16 v[14:17], v[134:137], v[240:243], v[14:17]
	v_mfma_f32_16x16x32_bf16 v[10:13], v[142:145], v[240:243], v[10:13]
	s_setprio 0
	s_setprio 1
	v_mfma_f32_16x16x32_bf16 v[54:57], v[170:173], v[210:213], v[54:57]
	v_mfma_f32_16x16x32_bf16 v[50:53], v[202:205], v[210:213], v[50:53]
	v_mfma_f32_16x16x32_bf16 v[38:41], v[170:173], v[220:223], v[38:41]
	v_mfma_f32_16x16x32_bf16 v[34:37], v[202:205], v[220:223], v[34:37]
	v_mfma_f32_16x16x32_bf16 v[22:25], v[170:173], v[228:231], v[22:25]
	v_mfma_f32_16x16x32_bf16 v[18:21], v[202:205], v[228:231], v[18:21]
	v_mfma_f32_16x16x32_bf16 v[6:9], v[170:173], v[236:239], v[6:9]
	v_mfma_f32_16x16x32_bf16 v[2:5], v[202:205], v[236:239], v[2:5]
	v_mfma_f32_16x16x32_bf16 v[54:57], v[174:177], v[216:219], v[54:57]
	v_mfma_f32_16x16x32_bf16 v[50:53], v[206:209], v[216:219], v[50:53]
	v_mfma_f32_16x16x32_bf16 v[38:41], v[174:177], v[224:227], v[38:41]
	v_mfma_f32_16x16x32_bf16 v[34:37], v[206:209], v[224:227], v[34:37]
	v_mfma_f32_16x16x32_bf16 v[22:25], v[174:177], v[232:235], v[22:25]
	v_mfma_f32_16x16x32_bf16 v[18:21], v[206:209], v[232:235], v[18:21]
	v_mfma_f32_16x16x32_bf16 v[6:9], v[174:177], v[240:243], v[6:9]
	v_mfma_f32_16x16x32_bf16 v[2:5], v[206:209], v[240:243], v[2:5]
	s_setprio 0
	s_barrier
	s_add_i32 m0, s30, 0x2000
	s_nop 0
	global_load_lds_dwordx4 v158, s[42:43]
	s_add_i32 s30, 0, 0x18000
	v_add_u32_e32 v0, s30, v197
	s_add_i32 s31, 0, 0x1c000
	ds_read_b128 v[130:133], v0
	ds_read_b128 v[134:137], v0 offset:1024
	ds_read_b128 v[138:141], v0 offset:2048
	ds_read_b128 v[142:145], v0 offset:3072
	v_add_u32_e32 v0, s31, v197
	ds_read_b128 v[170:173], v0
	ds_read_b128 v[174:177], v0 offset:1024
	ds_read_b128 v[202:205], v0 offset:2048
	ds_read_b128 v[206:209], v0 offset:3072
	s_add_u32 s12, s12, 0x40000
	s_addc_u32 s13, s13, 0
	s_mov_b32 m0, s63
	ds_read_b128 v[210:213], v200 offset:32768
	ds_read_b128 v[216:219], v200 offset:33792
	ds_read_b128 v[220:223], v200 offset:34816
	ds_read_b128 v[224:227], v200 offset:35840
	ds_read_b128 v[228:231], v200 offset:36864
	ds_read_b128 v[232:235], v200 offset:37888
	ds_read_b128 v[236:239], v200 offset:38912
	ds_read_b128 v[240:243], v200 offset:39936
	global_load_lds_dwordx4 v152, s[12:13]
	s_mov_b32 m0, s64
	s_nop 0
	global_load_lds_dwordx4 v156, s[12:13]
	s_waitcnt vmcnt(8)
	s_waitcnt lgkmcnt(0)
	s_barrier
	s_setprio 1
	s_waitcnt lgkmcnt(0)
	v_mfma_f32_16x16x32_bf16 v[126:129], v[130:133], v[210:213], v[126:129]
	v_mfma_f32_16x16x32_bf16 v[122:125], v[138:141], v[210:213], v[122:125]
	v_mfma_f32_16x16x32_bf16 v[110:113], v[130:133], v[220:223], v[110:113]
	v_mfma_f32_16x16x32_bf16 v[106:109], v[138:141], v[220:223], v[106:109]
	v_mfma_f32_16x16x32_bf16 v[94:97], v[130:133], v[228:231], v[94:97]
	v_mfma_f32_16x16x32_bf16 v[90:93], v[138:141], v[228:231], v[90:93]
	v_mfma_f32_16x16x32_bf16 v[78:81], v[130:133], v[236:239], v[78:81]
	v_mfma_f32_16x16x32_bf16 v[74:77], v[138:141], v[236:239], v[74:77]
	v_mfma_f32_16x16x32_bf16 v[126:129], v[134:137], v[216:219], v[126:129]
	v_mfma_f32_16x16x32_bf16 v[122:125], v[142:145], v[216:219], v[122:125]
	v_mfma_f32_16x16x32_bf16 v[110:113], v[134:137], v[224:227], v[110:113]
	v_mfma_f32_16x16x32_bf16 v[106:109], v[142:145], v[224:227], v[106:109]
	v_mfma_f32_16x16x32_bf16 v[94:97], v[134:137], v[232:235], v[94:97]
	v_mfma_f32_16x16x32_bf16 v[90:93], v[142:145], v[232:235], v[90:93]
	v_mfma_f32_16x16x32_bf16 v[78:81], v[134:137], v[240:243], v[78:81]
	v_mfma_f32_16x16x32_bf16 v[74:77], v[142:145], v[240:243], v[74:77]
	s_setprio 0
	s_setprio 1
	v_mfma_f32_16x16x32_bf16 v[118:121], v[170:173], v[210:213], v[118:121]
	v_mfma_f32_16x16x32_bf16 v[114:117], v[202:205], v[210:213], v[114:117]
	v_mfma_f32_16x16x32_bf16 v[102:105], v[170:173], v[220:223], v[102:105]
	v_mfma_f32_16x16x32_bf16 v[98:101], v[202:205], v[220:223], v[98:101]
	v_mfma_f32_16x16x32_bf16 v[86:89], v[170:173], v[228:231], v[86:89]
	v_mfma_f32_16x16x32_bf16 v[82:85], v[202:205], v[228:231], v[82:85]
	v_mfma_f32_16x16x32_bf16 v[70:73], v[170:173], v[236:239], v[70:73]
	v_mfma_f32_16x16x32_bf16 v[66:69], v[202:205], v[236:239], v[66:69]
	v_mfma_f32_16x16x32_bf16 v[118:121], v[174:177], v[216:219], v[118:121]
	v_mfma_f32_16x16x32_bf16 v[114:117], v[206:209], v[216:219], v[114:117]
	v_mfma_f32_16x16x32_bf16 v[102:105], v[174:177], v[224:227], v[102:105]
	v_mfma_f32_16x16x32_bf16 v[98:101], v[206:209], v[224:227], v[98:101]
	v_mfma_f32_16x16x32_bf16 v[86:89], v[174:177], v[232:235], v[86:89]
	v_mfma_f32_16x16x32_bf16 v[82:85], v[206:209], v[232:235], v[82:85]
	v_mfma_f32_16x16x32_bf16 v[70:73], v[174:177], v[240:243], v[70:73]
	v_mfma_f32_16x16x32_bf16 v[66:69], v[206:209], v[240:243], v[66:69]
	s_setprio 0
	s_barrier
	s_add_i32 m0, s30, s61
	s_add_u32 s42, s10, 0x80
	s_addc_u32 s43, s11, 0
	ds_read_b128 v[210:213], v200 offset:49152
	ds_read_b128 v[216:219], v200 offset:50176
	ds_read_b128 v[220:223], v200 offset:51200
	ds_read_b128 v[224:227], v200 offset:52224
	ds_read_b128 v[228:231], v200 offset:53248
	ds_read_b128 v[232:235], v200 offset:54272
	ds_read_b128 v[236:239], v200 offset:55296
	ds_read_b128 v[240:243], v200 offset:56320
	global_load_lds_dwordx4 v154, s[42:43]
	s_add_i32 m0, m0, 0x2000
	s_add_u32 s10, s10, 0x40080
	s_addc_u32 s11, s11, 0
	global_load_lds_dwordx4 v158, s[42:43]
	s_add_i32 m0, s31, s61
	s_add_u32 s42, s12, 0xfffc0080
	s_addc_u32 s43, s13, -1
	global_load_lds_dwordx4 v154, s[10:11]
	s_add_i32 m0, m0, 0x2000
	s_nop 0
	global_load_lds_dwordx4 v158, s[10:11]
	s_mov_b32 m0, s66
	s_nop 0
	global_load_lds_dwordx4 v152, s[42:43]
	s_mov_b32 m0, s67
	s_add_i32 s12, s31, s61
	global_load_lds_dwordx4 v156, s[42:43]
	s_waitcnt vmcnt(8)
	s_waitcnt lgkmcnt(0)
	s_barrier
	s_setprio 1
	s_waitcnt lgkmcnt(0)
	v_mfma_f32_16x16x32_bf16 v[62:65], v[130:133], v[210:213], v[62:65]
	v_mfma_f32_16x16x32_bf16 v[58:61], v[138:141], v[210:213], v[58:61]
	v_mfma_f32_16x16x32_bf16 v[46:49], v[130:133], v[220:223], v[46:49]
	v_mfma_f32_16x16x32_bf16 v[42:45], v[138:141], v[220:223], v[42:45]
	v_mfma_f32_16x16x32_bf16 v[30:33], v[130:133], v[228:231], v[30:33]
	v_mfma_f32_16x16x32_bf16 v[26:29], v[138:141], v[228:231], v[26:29]
	v_mfma_f32_16x16x32_bf16 v[14:17], v[130:133], v[236:239], v[14:17]
	v_mfma_f32_16x16x32_bf16 v[10:13], v[138:141], v[236:239], v[10:13]
	v_mfma_f32_16x16x32_bf16 v[62:65], v[134:137], v[216:219], v[62:65]
	v_mfma_f32_16x16x32_bf16 v[58:61], v[142:145], v[216:219], v[58:61]
	v_mfma_f32_16x16x32_bf16 v[46:49], v[134:137], v[224:227], v[46:49]
	v_mfma_f32_16x16x32_bf16 v[42:45], v[142:145], v[224:227], v[42:45]
	v_mfma_f32_16x16x32_bf16 v[30:33], v[134:137], v[232:235], v[30:33]
	v_mfma_f32_16x16x32_bf16 v[26:29], v[142:145], v[232:235], v[26:29]
	v_mfma_f32_16x16x32_bf16 v[14:17], v[134:137], v[240:243], v[14:17]
	v_mfma_f32_16x16x32_bf16 v[10:13], v[142:145], v[240:243], v[10:13]
	s_setprio 0
	s_setprio 1
	v_mfma_f32_16x16x32_bf16 v[54:57], v[170:173], v[210:213], v[54:57]
	v_mfma_f32_16x16x32_bf16 v[50:53], v[202:205], v[210:213], v[50:53]
	v_mfma_f32_16x16x32_bf16 v[38:41], v[170:173], v[220:223], v[38:41]
	v_mfma_f32_16x16x32_bf16 v[34:37], v[202:205], v[220:223], v[34:37]
	v_mfma_f32_16x16x32_bf16 v[22:25], v[170:173], v[228:231], v[22:25]
	v_mfma_f32_16x16x32_bf16 v[18:21], v[202:205], v[228:231], v[18:21]
	v_mfma_f32_16x16x32_bf16 v[6:9], v[170:173], v[236:239], v[6:9]
	v_mfma_f32_16x16x32_bf16 v[2:5], v[202:205], v[236:239], v[2:5]
	v_mfma_f32_16x16x32_bf16 v[54:57], v[174:177], v[216:219], v[54:57]
	v_mfma_f32_16x16x32_bf16 v[50:53], v[206:209], v[216:219], v[50:53]
	v_mfma_f32_16x16x32_bf16 v[38:41], v[174:177], v[224:227], v[38:41]
	v_mfma_f32_16x16x32_bf16 v[34:37], v[206:209], v[224:227], v[34:37]
	v_mfma_f32_16x16x32_bf16 v[22:25], v[174:177], v[232:235], v[22:25]
	v_mfma_f32_16x16x32_bf16 v[18:21], v[206:209], v[232:235], v[18:21]
	v_mfma_f32_16x16x32_bf16 v[6:9], v[174:177], v[240:243], v[6:9]
	v_mfma_f32_16x16x32_bf16 v[2:5], v[206:209], v[240:243], v[2:5]
	s_setprio 0
	s_barrier
	s_add_i32 s29, s29, 2
	s_add_u32 s8, s8, 0x100
	s_addc_u32 s9, s9, 0
	s_add_u32 s27, s27, 0x100
	s_addc_u32 s28, s28, 0
	s_cmp_gt_u32 s29, 13
	s_cbranch_scc0 .LBB0_170
	s_and_b64 vcc, exec, s[46:47]
	s_cbranch_vccz .LBB0_173
	s_barrier
